# attnB tile loop hand-scheduled: K fragments read up front, V fragments prefetched under QK, band mask only where needed, fully masked wave tiles skipped; attnA loop as v4
# baseline (speedup 1.0000x reference)
.LBB0_460:
	s_add_i32 s26, s27, 1
	s_cmp_ge_i32 s26, s22
	s_cselect_b64 s[20:21], -1, 0
	s_bitcmp1_b32 s27, 0
	s_cselect_b32 s3, 0x2400, 0
	v_add_u32_e32 v67, s3, v172
	s_cmp_ge_i32 s27, s17
	s_cbranch_scc1 .Lattn_b_go
	v_readfirstlane_b32 s3, v175
	s_nop 3
	s_cmp_ge_i32 s3, 31
	s_cbranch_scc1 .Lattn_b_skip
	s_cmp_lt_i32 s3, 0xfffffebf
	s_cbranch_scc1 .Lattn_b_skip
.Lattn_b_go:
	ds_read_b128 v[34:37], v67
	ds_read_b128 v[38:41], v67 offset:4608
	ds_read_b128 v[42:45], v67 offset:32
	ds_read_b128 v[46:49], v67 offset:4640
	ds_read_b128 v[50:53], v67 offset:64
	ds_read_b128 v[54:57], v67 offset:4672
	ds_read_b128 v[58:61], v67 offset:96
	ds_read_b128 v[62:65], v67 offset:4704
	s_bitcmp1_b32 s26, 0
	s_cselect_b32 s3, 0x2400, 0
	v_add_u32_e32 v254, s3, v170
	v_add_u32_e32 v255, s3, v171
	v_add_u32_e32 v255, 0x4800, v255
	s_waitcnt vmcnt(0)
	ds_write_b128 v254, v[148:151]
	ds_write2_b64 v255, v[152:153], v[154:155] offset1:2
	s_add_i32 s28, s27, 2
	s_add_i32 s3, s16, s27
	s_add_i32 s3, s3, 2
	s_add_i32 s29, s25, s27
	s_cmp_lt_i32 s28, s17
	s_cselect_b32 s3, s3, s29
	s_lshl_b32 s28, s3, 6
	s_cmp_lt_i32 s3, 64
	s_cselect_b32 s3, s24, s23
	s_add_i32 s3, s3, s28
	v_add_u32_e32 v248, s3, v157
	v_mad_i64_i32 v[250:251], s[30:31], v248, s60, v[166:167]
	s_ashr_i32 s29, s28, 31
	v_lshl_add_u64 v[252:253], s[28:29], 1, v[168:169]
	global_load_dwordx4 v[148:151], v[250:251], off
	global_load_dwordx4 v[152:155], v[252:253], off
	s_waitcnt lgkmcnt(9)
	v_mfma_f32_32x32x16_bf16 v[100:115], v[34:37], v[132:135], v[84:99]
	ds_read_b128 v[34:37], v67 offset:18432
	s_waitcnt lgkmcnt(9)
	v_mfma_f32_32x32x16_bf16 v[116:131], v[38:41], v[132:135], v[84:99]
	ds_read_b128 v[38:41], v67 offset:23040
	s_waitcnt lgkmcnt(9)
	v_mfma_f32_32x32x16_bf16 v[100:115], v[42:45], v[136:139], v[100:115]
	ds_read_b128 v[42:45], v67 offset:18464
	s_waitcnt lgkmcnt(9)
	v_mfma_f32_32x32x16_bf16 v[116:131], v[46:49], v[136:139], v[116:131]
	ds_read_b128 v[46:49], v67 offset:23072
	s_waitcnt lgkmcnt(9)
	v_mfma_f32_32x32x16_bf16 v[100:115], v[50:53], v[140:143], v[100:115]
	ds_read_b128 v[50:53], v67 offset:18496
	s_waitcnt lgkmcnt(9)
	v_mfma_f32_32x32x16_bf16 v[116:131], v[54:57], v[140:143], v[116:131]
	ds_read_b128 v[54:57], v67 offset:23104
	s_waitcnt lgkmcnt(9)
	v_mfma_f32_32x32x16_bf16 v[100:115], v[58:61], v[144:147], v[100:115]
	ds_read_b128 v[58:61], v67 offset:18528
	s_waitcnt lgkmcnt(9)
	v_mfma_f32_32x32x16_bf16 v[116:131], v[62:65], v[144:147], v[116:131]
	ds_read_b128 v[62:65], v67 offset:23136
	s_cmp_ge_i32 s27, s17
	s_cbranch_scc1 .Lattn_b_max
	v_readfirstlane_b32 s3, v175
	s_nop 3
	s_addk_i32 s3, 0xe2
	s_cmp_lt_u32 s3, 0xa3
	s_cbranch_scc1 .Lattn_b_max
	s_nop 7
	v_cmp_lt_u32_e32 vcc, s61, v175
	v_add_u32_e32 v176, 32, v175
	s_nop 5
	v_cndmask_b32_e32 v100, v226, v100, vcc
	v_cmp_lt_u32_e32 vcc, s61, v176
	v_add_u32_e32 v176, 1, v175
	s_nop 0
	v_cndmask_b32_e32 v116, v226, v116, vcc
	v_cmp_lt_u32_e32 vcc, s61, v176
	v_add_u32_e32 v176, 33, v175
	s_nop 0
	v_cndmask_b32_e32 v101, v226, v101, vcc
	v_cmp_lt_u32_e32 vcc, s61, v176
	v_add_u32_e32 v176, 2, v175
	s_nop 0
	v_cndmask_b32_e32 v117, v226, v117, vcc
	v_cmp_lt_u32_e32 vcc, s61, v176
	v_add_u32_e32 v176, 34, v175
	s_nop 0
	v_cndmask_b32_e32 v102, v226, v102, vcc
	v_cmp_lt_u32_e32 vcc, s61, v176
	v_add_u32_e32 v176, 3, v175
	s_nop 0
	v_cndmask_b32_e32 v118, v226, v118, vcc
	v_cmp_lt_u32_e32 vcc, s61, v176
	v_add_u32_e32 v176, 35, v175
	s_nop 0
	v_cndmask_b32_e32 v103, v226, v103, vcc
	v_cmp_lt_u32_e32 vcc, s61, v176
	v_add_u32_e32 v176, 8, v175
	s_nop 0
	v_cndmask_b32_e32 v119, v226, v119, vcc
	v_cmp_lt_u32_e32 vcc, s61, v176
	v_add_u32_e32 v176, 40, v175
	s_nop 0
	v_cndmask_b32_e32 v104, v226, v104, vcc
	v_cmp_lt_u32_e32 vcc, s61, v176
	v_add_u32_e32 v176, 9, v175
	s_nop 0
	v_cndmask_b32_e32 v120, v226, v120, vcc
	v_cmp_lt_u32_e32 vcc, s61, v176
	v_add_u32_e32 v176, 41, v175
	s_nop 0
	v_cndmask_b32_e32 v105, v226, v105, vcc
	v_cmp_lt_u32_e32 vcc, s61, v176
	v_add_u32_e32 v176, 10, v175
	s_nop 0
	v_cndmask_b32_e32 v121, v226, v121, vcc
	v_cmp_lt_u32_e32 vcc, s61, v176
	v_add_u32_e32 v176, 42, v175
	s_nop 0
	v_cndmask_b32_e32 v106, v226, v106, vcc
	v_cmp_lt_u32_e32 vcc, s61, v176
	v_add_u32_e32 v176, 11, v175
	s_nop 0
	v_cndmask_b32_e32 v122, v226, v122, vcc
	v_cmp_lt_u32_e32 vcc, s61, v176
	v_add_u32_e32 v176, 43, v175
	s_nop 0
	v_cndmask_b32_e32 v107, v226, v107, vcc
	v_cmp_lt_u32_e32 vcc, s61, v176
	v_add_u32_e32 v176, 16, v175
	s_nop 0
	v_cndmask_b32_e32 v123, v226, v123, vcc
	v_cmp_lt_u32_e32 vcc, s61, v176
	v_add_u32_e32 v176, 48, v175
	s_nop 0
	v_cndmask_b32_e32 v108, v226, v108, vcc
	v_cmp_lt_u32_e32 vcc, s61, v176
	v_add_u32_e32 v176, 17, v175
	s_nop 0
	v_cndmask_b32_e32 v124, v226, v124, vcc
	v_cmp_lt_u32_e32 vcc, s61, v176
	v_add_u32_e32 v176, 49, v175
	s_nop 0
	v_cndmask_b32_e32 v109, v226, v109, vcc
	v_cmp_lt_u32_e32 vcc, s61, v176
	v_add_u32_e32 v176, 18, v175
	s_nop 0
	v_cndmask_b32_e32 v125, v226, v125, vcc
	v_cmp_lt_u32_e32 vcc, s61, v176
	v_add_u32_e32 v176, 50, v175
	s_nop 0
	v_cndmask_b32_e32 v110, v226, v110, vcc
	v_cmp_lt_u32_e32 vcc, s61, v176
	v_add_u32_e32 v176, 19, v175
	s_nop 0
	v_cndmask_b32_e32 v126, v226, v126, vcc
	v_cmp_lt_u32_e32 vcc, s61, v176
	v_add_u32_e32 v176, 51, v175
	s_nop 0
	v_cndmask_b32_e32 v111, v226, v111, vcc
	v_cmp_lt_u32_e32 vcc, s61, v176
	v_add_u32_e32 v176, 24, v175
	s_nop 0
	v_cndmask_b32_e32 v127, v226, v127, vcc
	v_cmp_lt_u32_e32 vcc, s61, v176
	v_add_u32_e32 v176, 56, v175
	s_nop 0
	v_cndmask_b32_e32 v112, v226, v112, vcc
	v_cmp_lt_u32_e32 vcc, s61, v176
	v_add_u32_e32 v176, 25, v175
	s_nop 0
	v_cndmask_b32_e32 v128, v226, v128, vcc
	v_cmp_lt_u32_e32 vcc, s61, v176
	v_add_u32_e32 v176, 57, v175
	s_nop 0
	v_cndmask_b32_e32 v113, v226, v113, vcc
	v_cmp_lt_u32_e32 vcc, s61, v176
	v_add_u32_e32 v176, 26, v175
	s_nop 0
	v_cndmask_b32_e32 v129, v226, v129, vcc
	v_cmp_lt_u32_e32 vcc, s61, v176
	v_add_u32_e32 v176, 58, v175
	s_nop 0
	v_cndmask_b32_e32 v114, v226, v114, vcc
	v_cmp_lt_u32_e32 vcc, s61, v176
	v_add_u32_e32 v176, 27, v175
	s_nop 0
	v_cndmask_b32_e32 v130, v226, v130, vcc
	v_cmp_lt_u32_e32 vcc, s61, v176
	v_add_u32_e32 v176, 59, v175
	s_nop 0
	v_cndmask_b32_e32 v115, v226, v115, vcc
	v_cmp_lt_u32_e32 vcc, s61, v176
	s_nop 1
	v_cndmask_b32_e32 v131, v226, v131, vcc
.Lattn_b_max:
	s_nop 9
	v_max3_f32 v244, v100, v101, v102
	v_max3_f32 v245, v103, v104, v105
	v_max3_f32 v244, v244, v106, v107
	v_max3_f32 v245, v245, v108, v109
	v_max3_f32 v244, v244, v110, v111
	v_max3_f32 v245, v245, v112, v113
	v_max3_f32 v244, v244, v114, v115
	v_max3_f32 v246, v116, v117, v118
	v_max3_f32 v247, v119, v120, v121
	v_max3_f32 v246, v246, v122, v123
	v_max3_f32 v247, v247, v124, v125
	v_max3_f32 v246, v246, v126, v127
	v_max3_f32 v247, v247, v128, v129
	v_max3_f32 v246, v246, v130, v131
	v_max3_f32 v244, v244, v245, v246
	v_max_f32_e32 v244, v244, v247
	v_mov_b32_e32 v245, v244
	s_nop 1
	v_permlane32_swap_b32_e32 v244, v245
	v_max_f32_e32 v244, v244, v245
	v_cmp_lt_f32_e32 vcc, s52, v244
	s_cbranch_vccnz .Lattn_b_rescale
.Lattn_b_exp:
	v_exp_f32_e32 v100, v100
	v_exp_f32_e32 v101, v101
	v_exp_f32_e32 v102, v102
	v_exp_f32_e32 v103, v103
	v_exp_f32_e32 v104, v104
	v_exp_f32_e32 v105, v105
	v_exp_f32_e32 v106, v106
	v_exp_f32_e32 v107, v107
	v_cvt_pk_bf16_f32 v100, v100, v101
	v_cvt_pk_bf16_f32 v101, v102, v103
	v_cvt_pk_bf16_f32 v102, v104, v105
	v_cvt_pk_bf16_f32 v103, v106, v107
	s_mov_b32 s65, s64
	v_mov_b64_e32 v[176:177], s[64:65]
	v_mov_b64_e32 v[178:179], s[64:65]
	s_waitcnt lgkmcnt(7)
	v_mfma_f32_32x32x16_bf16 v[2:17], v[34:37], v[100:103], v[2:17]
	v_exp_f32_e32 v108, v108
	v_exp_f32_e32 v109, v109
	v_exp_f32_e32 v110, v110
	v_exp_f32_e32 v111, v111
	s_waitcnt lgkmcnt(6)
	v_mfma_f32_32x32x16_bf16 v[18:33], v[38:41], v[100:103], v[18:33]
	v_exp_f32_e32 v112, v112
	v_exp_f32_e32 v113, v113
	v_exp_f32_e32 v114, v114
	v_exp_f32_e32 v115, v115
	v_cvt_pk_bf16_f32 v104, v108, v109
	v_cvt_pk_bf16_f32 v105, v110, v111
	v_cvt_pk_bf16_f32 v106, v112, v113
	v_cvt_pk_bf16_f32 v107, v114, v115
	s_nop 1
	s_waitcnt lgkmcnt(5)
	v_mfma_f32_32x32x16_bf16 v[2:17], v[42:45], v[104:107], v[2:17]
	v_exp_f32_e32 v116, v116
	v_exp_f32_e32 v117, v117
	v_exp_f32_e32 v118, v118
	v_exp_f32_e32 v119, v119
	s_waitcnt lgkmcnt(4)
	v_mfma_f32_32x32x16_bf16 v[18:33], v[46:49], v[104:107], v[18:33]
	v_exp_f32_e32 v120, v120
	v_exp_f32_e32 v121, v121
	v_exp_f32_e32 v122, v122
	v_exp_f32_e32 v123, v123
	v_cvt_pk_bf16_f32 v108, v116, v117
	v_cvt_pk_bf16_f32 v109, v118, v119
	v_cvt_pk_bf16_f32 v110, v120, v121
	v_cvt_pk_bf16_f32 v111, v122, v123
	s_nop 1
	s_waitcnt lgkmcnt(3)
	v_mfma_f32_32x32x16_bf16 v[2:17], v[50:53], v[108:111], v[2:17]
	v_exp_f32_e32 v124, v124
	v_exp_f32_e32 v125, v125
	v_exp_f32_e32 v126, v126
	v_exp_f32_e32 v127, v127
	s_waitcnt lgkmcnt(2)
	v_mfma_f32_32x32x16_bf16 v[18:33], v[54:57], v[108:111], v[18:33]
	v_exp_f32_e32 v128, v128
	v_exp_f32_e32 v129, v129
	v_exp_f32_e32 v130, v130
	v_exp_f32_e32 v131, v131
	v_cvt_pk_bf16_f32 v112, v124, v125
	v_cvt_pk_bf16_f32 v113, v126, v127
	v_cvt_pk_bf16_f32 v114, v128, v129
	v_cvt_pk_bf16_f32 v115, v130, v131
	s_nop 1
	s_waitcnt lgkmcnt(1)
	v_mfma_f32_32x32x16_bf16 v[2:17], v[58:61], v[112:115], v[2:17]
	s_waitcnt lgkmcnt(0)
	s_barrier
	v_mfma_f32_32x32x16_bf16 v[18:33], v[62:65], v[112:115], v[18:33]
	v_mfma_f32_32x32x16_bf16 v[68:83], v[176:179], v[100:103], v[68:83]
	v_mfma_f32_32x32x16_bf16 v[68:83], v[176:179], v[104:107], v[68:83]
	v_mfma_f32_32x32x16_bf16 v[68:83], v[176:179], v[108:111], v[68:83]
	v_mfma_f32_32x32x16_bf16 v[68:83], v[176:179], v[112:115], v[68:83]
.Lattn_b_next:
	v_add_u32_e32 v175, 64, v175
	s_and_b64 vcc, exec, s[20:21]
	s_cbranch_vccnz .Lattn_b_exit
	s_mov_b32 s27, s26
	s_branch .LBB0_460
.Lattn_b_skip:
	s_bitcmp1_b32 s26, 0
	s_cselect_b32 s3, 0x2400, 0
	v_add_u32_e32 v254, s3, v170
	v_add_u32_e32 v255, s3, v171
	v_add_u32_e32 v255, 0x4800, v255
	s_waitcnt vmcnt(0)
	ds_write_b128 v254, v[148:151]
	ds_write2_b64 v255, v[152:153], v[154:155] offset1:2
	s_add_i32 s28, s27, 2
	s_add_i32 s3, s16, s27
	s_add_i32 s3, s3, 2
	s_add_i32 s29, s25, s27
	s_cmp_lt_i32 s28, s17
	s_cselect_b32 s3, s3, s29
	s_lshl_b32 s28, s3, 6
	s_cmp_lt_i32 s3, 64
	s_cselect_b32 s3, s24, s23
	s_add_i32 s3, s3, s28
	v_add_u32_e32 v248, s3, v157
	v_mad_i64_i32 v[250:251], s[30:31], v248, s60, v[166:167]
	s_ashr_i32 s29, s28, 31
	v_lshl_add_u64 v[252:253], s[28:29], 1, v[168:169]
	global_load_dwordx4 v[148:151], v[250:251], off
	global_load_dwordx4 v[152:155], v[252:253], off
	s_waitcnt lgkmcnt(0)
	s_barrier
	s_branch .Lattn_b_next
.Lattn_b_exit:
	s_waitcnt vmcnt(0)
	s_nop 11
	v_mov_b64_e32 v[34:35], v[2:3]
	v_mov_b64_e32 v[36:37], v[4:5]
	v_mov_b64_e32 v[38:39], v[6:7]
	v_mov_b64_e32 v[40:41], v[8:9]
	v_mov_b64_e32 v[42:43], v[10:11]
	v_mov_b64_e32 v[44:45], v[12:13]
	v_mov_b64_e32 v[46:47], v[14:15]
	v_mov_b64_e32 v[48:49], v[16:17]
	v_mov_b64_e32 v[50:51], v[18:19]
	v_mov_b64_e32 v[52:53], v[20:21]
	v_mov_b64_e32 v[54:55], v[22:23]
	v_mov_b64_e32 v[56:57], v[24:25]
	v_mov_b64_e32 v[58:59], v[26:27]
	v_mov_b64_e32 v[60:61], v[28:29]
	v_mov_b64_e32 v[62:63], v[30:31]
	v_mov_b64_e32 v[64:65], v[32:33]
	s_branch .LBB0_449
.Lattn_b_rescale:
	v_max_f32_e32 v245, 0, v244
	v_exp_f32_e64 v246, -v245
	v_add_f32_e32 v163, v163, v245
	v_sub_f32_e32 v100, v100, v245
	v_sub_f32_e32 v101, v101, v245
	v_sub_f32_e32 v102, v102, v245
	v_sub_f32_e32 v103, v103, v245
	v_sub_f32_e32 v104, v104, v245
	v_sub_f32_e32 v105, v105, v245
	v_sub_f32_e32 v106, v106, v245
	v_sub_f32_e32 v107, v107, v245
	v_sub_f32_e32 v108, v108, v245
	v_sub_f32_e32 v109, v109, v245
	v_sub_f32_e32 v110, v110, v245
	v_sub_f32_e32 v111, v111, v245
	v_sub_f32_e32 v112, v112, v245
	v_sub_f32_e32 v113, v113, v245
	v_sub_f32_e32 v114, v114, v245
	v_sub_f32_e32 v115, v115, v245
	v_sub_f32_e32 v116, v116, v245
	v_sub_f32_e32 v117, v117, v245
	v_sub_f32_e32 v118, v118, v245
	v_sub_f32_e32 v119, v119, v245
	v_sub_f32_e32 v120, v120, v245
	v_sub_f32_e32 v121, v121, v245
	v_sub_f32_e32 v122, v122, v245
	v_sub_f32_e32 v123, v123, v245
	v_sub_f32_e32 v124, v124, v245
	v_sub_f32_e32 v125, v125, v245
	v_sub_f32_e32 v126, v126, v245
	v_sub_f32_e32 v127, v127, v245
	v_sub_f32_e32 v128, v128, v245
	v_sub_f32_e32 v129, v129, v245
	v_sub_f32_e32 v130, v130, v245
	v_sub_f32_e32 v131, v131, v245
	v_mul_f32_e32 v2, v2, v246
	v_mul_f32_e32 v3, v3, v246
	v_mul_f32_e32 v4, v4, v246
	v_mul_f32_e32 v5, v5, v246
	v_mul_f32_e32 v6, v6, v246
	v_mul_f32_e32 v7, v7, v246
	v_mul_f32_e32 v8, v8, v246
	v_mul_f32_e32 v9, v9, v246
	v_mul_f32_e32 v10, v10, v246
	v_mul_f32_e32 v11, v11, v246
	v_mul_f32_e32 v12, v12, v246
	v_mul_f32_e32 v13, v13, v246
	v_mul_f32_e32 v14, v14, v246
	v_mul_f32_e32 v15, v15, v246
	v_mul_f32_e32 v16, v16, v246
	v_mul_f32_e32 v17, v17, v246
	v_mul_f32_e32 v18, v18, v246
	v_mul_f32_e32 v19, v19, v246
	v_mul_f32_e32 v20, v20, v246
	v_mul_f32_e32 v21, v21, v246
	v_mul_f32_e32 v22, v22, v246
	v_mul_f32_e32 v23, v23, v246
	v_mul_f32_e32 v24, v24, v246
	v_mul_f32_e32 v25, v25, v246
	v_mul_f32_e32 v26, v26, v246
	v_mul_f32_e32 v27, v27, v246
	v_mul_f32_e32 v28, v28, v246
	v_mul_f32_e32 v29, v29, v246
	v_mul_f32_e32 v30, v30, v246
	v_mul_f32_e32 v31, v31, v246
	v_mul_f32_e32 v32, v32, v246
	v_mul_f32_e32 v33, v33, v246
	v_mul_f32_e32 v68, v68, v246
	v_mul_f32_e32 v69, v69, v246
	v_mul_f32_e32 v70, v70, v246
	v_mul_f32_e32 v71, v71, v246
	v_mul_f32_e32 v72, v72, v246
	v_mul_f32_e32 v73, v73, v246
	v_mul_f32_e32 v74, v74, v246
	v_mul_f32_e32 v75, v75, v246
	v_mul_f32_e32 v76, v76, v246
	v_mul_f32_e32 v77, v77, v246
	v_mul_f32_e32 v78, v78, v246
	v_mul_f32_e32 v79, v79, v246
	v_mul_f32_e32 v80, v80, v246
	v_mul_f32_e32 v81, v81, v246
	v_mul_f32_e32 v82, v82, v246
	v_mul_f32_e32 v83, v83, v246
	v_xor_b32_e32 v84, 0x80000000, v163
	v_mov_b32_e32 v85, v84
	v_mov_b32_e32 v86, v84
	v_mov_b32_e32 v87, v84
	v_mov_b32_e32 v88, v84
	v_mov_b32_e32 v89, v84
	v_mov_b32_e32 v90, v84
	v_mov_b32_e32 v91, v84
	v_mov_b32_e32 v92, v84
	v_mov_b32_e32 v93, v84
	v_mov_b32_e32 v94, v84
	v_mov_b32_e32 v95, v84
	v_mov_b32_e32 v96, v84
	v_mov_b32_e32 v97, v84
	v_mov_b32_e32 v98, v84
	v_mov_b32_e32 v99, v84
	s_branch .Lattn_b_exp
